# v66: L1 invalidate of the invalidating seams issued by wave 1 in parallel with thread 0's arrival; all waves wait vmcnt(0) before the closing s_barrier
# baseline (speedup 1.0000x reference)
.LBB0_415:
	s_getreg_b32 s2, hwreg(HW_REG_XCC_ID, 0, 4)
	s_waitcnt vmcnt(0)
	s_waitcnt lgkmcnt(0)
	s_barrier
	v_readfirstlane_b32 s99, v160
	v_readlane_b32 s98, v255, 63
	s_lshr_b32 s99, s99, 6
	s_cmp_lg_u32 s99, 1
	s_cbranch_scc1 .Lwinv_skip_g1
	s_cmp_lg_u32 s98, 0
	s_cbranch_scc1 .Lwinv_skip_g1
	s_cmp_lg_u32 s33, 64
	s_cbranch_scc1 .Lwinv_skip_g1
	buffer_inv sc1
.Lwinv_skip_g1:
	s_and_saveexec_b64 s[0:1], s[14:15]
	s_cbranch_execz .LBB0_467
	v_readlane_b32 s98, v255, 63
	s_nop 0
	s_cmp_lg_u32 s98, 0
	s_cbranch_scc1 .Lhb_full_g1
	s_cmp_lg_u32 s33, 64
	s_cbranch_scc1 .Lhb_full_g1
	v_readlane_b32 s98, v255, 56
	v_readlane_b32 s100, v253, 1
	v_readlane_b32 s101, v253, 2
	v_readlane_b32 s99, v253, 0
	v_readlane_b32 vcc_lo, v254, 28
	s_add_i32 s98, s98, 1
	v_writelane_b32 v255, s98, 56
	s_lshl_b32 s99, s99, 14
	s_sub_u32 s100, s100, s99
	s_subb_u32 s101, s101, 0
	s_add_u32 s100, s100, 0xb000
	s_addc_u32 s101, s101, 0
	s_getreg_b32 s99, hwreg(HW_REG_XCC_ID, 0, 4)
	s_and_b32 s99, s99, 15
	s_lshl_b32 s99, s99, 8
	s_lshl_b32 vcc_hi, vcc_lo, 2
	s_add_i32 vcc_hi, vcc_hi, s99
	v_mov_b32_e32 v4, vcc_hi
	v_mov_b32_e32 v5, s98
	global_store_dword v4, v5, s[100:101]
	s_cmp_eq_u32 vcc_lo, 0
	s_cbranch_scc1 .Lhb_lead_g1
	s_lshr_b32 s99, s99, 2
	v_mov_b32_e32 v4, s99
	s_mov_b32 s99, 0

.LBB0_467:
	s_or_b64 exec, exec, s[0:1]
	s_waitcnt vmcnt(0)
	s_lshl_b32 s0, s18, 8
	v_writelane_b32 v255, s0, 10
	s_lshl_b32 s0, s18, 6
	s_lshl_b32 s90, s18, 2
	v_writelane_b32 v255, s0, 11
	v_readlane_b32 s0, v254, 43
	v_readlane_b32 s1, v254, 60
	s_add_u32 s0, s1, s0
	v_readlane_b32 s1, v254, 61
	s_addc_u32 s1, s1, 0
	s_add_u32 s0, s0, 0x1000
	s_addc_u32 s1, s1, 0
	v_writelane_b32 v255, s0, 12
	v_readlane_b32 s2, v254, 22
	v_readlane_b32 s4, v253, 39
	v_writelane_b32 v255, s1, 13
	s_lshl_b64 s[0:1], s[18:19], 2
	s_add_u32 s2, s2, s0
	v_readlane_b32 s0, v254, 23
	s_addc_u32 s3, s0, s1
	v_writelane_b32 v255, s2, 14
	s_waitcnt lgkmcnt(0)
	s_barrier
	v_writelane_b32 v255, s3, 15
	s_branch .LBB0_471

.LBB0_642:
	s_getreg_b32 s4, hwreg(HW_REG_XCC_ID, 0, 4)
	s_waitcnt vmcnt(0)
	s_barrier
	v_readfirstlane_b32 s99, v160
	v_readlane_b32 s98, v255, 63
	s_lshr_b32 s99, s99, 6
	s_cmp_lg_u32 s99, 1
	s_cbranch_scc1 .Lwinv_skip_g2
	s_cmp_lg_u32 s98, 0
	s_cbranch_scc1 .Lwinv_skip_g2
	s_cmp_lg_u32 s33, 64
	s_cbranch_scc1 .Lwinv_skip_g2
	buffer_inv sc1
.Lwinv_skip_g2:
	s_and_saveexec_b64 s[2:3], s[14:15]
	s_cbranch_execz .LBB0_694
	v_readlane_b32 s98, v255, 63
	s_nop 0
	s_cmp_lg_u32 s98, 0
	s_cbranch_scc1 .Llb_full_g2
	s_cmp_lg_u32 s33, 64
	s_cbranch_scc1 .Llb_full_g2
	v_readlane_b32 s98, v255, 56
	v_readlane_b32 s100, v253, 1
	v_readlane_b32 s101, v253, 2
	v_readlane_b32 s99, v253, 0
	v_readlane_b32 vcc_lo, v254, 28
	s_add_i32 s98, s98, 1
	v_writelane_b32 v255, s98, 56
	s_lshl_b32 s99, s99, 14
	s_sub_u32 s100, s100, s99
	s_subb_u32 s101, s101, 0
	s_add_u32 s100, s100, 0xb000
	s_addc_u32 s101, s101, 0
	s_getreg_b32 s99, hwreg(HW_REG_XCC_ID, 0, 4)
	s_and_b32 s99, s99, 15
	s_lshl_b32 s99, s99, 8
	s_lshl_b32 vcc_hi, vcc_lo, 2
	s_add_i32 vcc_hi, vcc_hi, s99
	v_mov_b32_e32 v4, vcc_hi
	v_mov_b32_e32 v5, s98
	global_store_dword v4, v5, s[100:101]
	s_cmp_eq_u32 vcc_lo, 0
	s_cbranch_scc1 .Llb_lead_g2
	s_lshr_b32 s99, s99, 2
	v_mov_b32_e32 v4, s99
	s_mov_b32 s99, 0

.LBB0_694:
	s_or_b64 exec, exec, s[2:3]
	s_waitcnt vmcnt(0)
	v_mov_b32_e32 v0, v160
	s_waitcnt lgkmcnt(0)
	s_barrier
	v_readlane_b32 s2, v254, 29
	v_ashrrev_i32_e32 v2, 6, v0
	s_nop 0
	v_add_u32_e32 v28, s2, v2
	v_cmp_gt_i32_e32 vcc, s51, v28
	s_and_saveexec_b64 s[2:3], vcc
	s_cbranch_execz .LBB0_697
	v_and_b32_e32 v3, 64, v202
	v_add_u32_e32 v3, 64, v3
	v_xor_b32_e32 v4, 32, v202
	v_cmp_lt_i32_e32 vcc, v4, v3
	v_lshlrev_b32_e32 v0, 3, v0
	v_and_b32_e32 v2, 0x1f8, v0
	v_cndmask_b32_e32 v4, v202, v4, vcc
	v_lshlrev_b32_e32 v29, 2, v4
	v_xor_b32_e32 v4, 16, v202
	v_cmp_lt_i32_e32 vcc, v4, v3
	v_readlane_b32 s4, v253, 42
	s_mov_b64 s[8:9], s[72:73]
	v_cndmask_b32_e32 v4, v202, v4, vcc
	v_lshlrev_b32_e32 v30, 2, v4
	v_xor_b32_e32 v4, 8, v202
	v_cmp_lt_i32_e32 vcc, v4, v3
	s_lshl_b32 s20, s18, 11
	v_mov_b32_e32 v5, v1
	v_cndmask_b32_e32 v4, v202, v4, vcc
	v_lshlrev_b32_e32 v31, 2, v4
	v_xor_b32_e32 v4, 4, v202
	v_cmp_lt_i32_e32 vcc, v4, v3
	v_readlane_b32 s5, v253, 43
	s_mov_b64 s[10:11], s[74:75]
	v_cndmask_b32_e32 v4, v202, v4, vcc
	v_lshlrev_b32_e32 v32, 2, v4
	v_xor_b32_e32 v4, 2, v202
	v_cmp_lt_i32_e32 vcc, v4, v3
	v_readlane_b32 s68, v253, 19
	v_readlane_b32 s76, v253, 27
	v_cndmask_b32_e32 v4, v202, v4, vcc
	v_lshlrev_b32_e32 v33, 2, v4
	v_xor_b32_e32 v4, 1, v202
	v_cmp_lt_i32_e32 vcc, v4, v3
	v_readlane_b32 s77, v253, 28
	v_readlane_b32 s78, v253, 29
	v_cndmask_b32_e32 v3, v202, v4, vcc
	v_lshlrev_b32_e32 v4, 1, v2
	v_lshl_add_u64 v[20:21], s[4:5], 0, v[4:5]
	s_lshl_b64 s[4:5], s[20:21], 2
	s_add_u32 s6, s76, s4
	s_addc_u32 s7, s77, s5
	v_readlane_b32 s72, v253, 23
	v_readlane_b32 s73, v253, 24
	v_readlane_b32 s74, v253, 25
	v_readlane_b32 s75, v253, 26
	v_readlane_b32 s79, v253, 30
	v_readlane_b32 s80, v253, 31
	v_readlane_b32 s81, v253, 32
	v_readlane_b32 s82, v253, 33
	v_readlane_b32 s83, v253, 34
	s_add_u32 s4, s78, s4
	v_lshlrev_b32_e32 v0, 2, v2
	v_readlane_b32 s82, v254, 56
	v_readlane_b32 s80, v254, 54
	s_mov_b64 s[74:75], s[10:11]
	s_addc_u32 s5, s79, s5
	v_lshl_add_u64 v[18:19], s[92:93], 0, v[0:1]
	v_lshlrev_b32_e32 v34, 2, v3
	v_readlane_b32 s83, v254, 57
	v_readlane_b32 s81, v254, 55
	s_mov_b64 s[72:73], s[8:9]
	v_lshl_add_u64 v[22:23], s[6:7], 0, v[0:1]
	v_lshl_add_u64 v[24:25], s[4:5], 0, v[0:1]
	s_mov_b64 s[4:5], 0
	v_lshlrev_b32_e32 v0, 2, v2
	v_readlane_b32 s69, v253, 20
	v_readlane_b32 s70, v253, 21
	v_readlane_b32 s71, v253, 22

.LBB0_780:
	s_getreg_b32 s2, hwreg(HW_REG_XCC_ID, 0, 4)
	s_waitcnt vmcnt(0)
	s_barrier
	v_readfirstlane_b32 s99, v160
	v_readlane_b32 s98, v255, 63
	s_lshr_b32 s99, s99, 6
	s_cmp_lg_u32 s99, 1
	s_cbranch_scc1 .Lwinv_skip_g3
	s_cmp_lg_u32 s98, 0
	s_cbranch_scc1 .Lwinv_skip_g3
	s_cmp_lg_u32 s33, 64
	s_cbranch_scc1 .Lwinv_skip_g3
	buffer_inv sc1

.LBB0_832:
	s_or_b64 exec, exec, s[0:1]
	s_waitcnt vmcnt(0)
	s_waitcnt lgkmcnt(0)
	v_mov_b32_e32 v2, v160
	s_barrier
	v_mov_b32_e32 v4, 0
	v_and_b32_e32 v3, 63, v2
	v_cmp_gt_u32_e64 s[2:3], 16, v3
	v_cmp_lt_u32_e32 vcc, 15, v3
	v_mov_b32_e32 v0, v3
	s_barrier
	s_and_saveexec_b64 s[0:1], vcc
	s_cbranch_execz .LBB0_852
	v_add_u32_e32 v0, -16, v3
	v_cmp_lt_u32_e32 vcc, 7, v0
	v_mov_b32_e32 v4, 1
	s_and_saveexec_b64 s[4:5], vcc
	s_cbranch_execz .LBB0_851
	v_subrev_u32_e32 v0, 24, v3
	v_cmp_lt_u32_e32 vcc, 4, v0
	v_mov_b32_e32 v4, 2
	s_and_saveexec_b64 s[6:7], vcc
	s_cbranch_execz .LBB0_850
	v_subrev_u32_e32 v0, 29, v3
	v_mov_b32_e32 v4, 3
	v_cmp_lt_u32_e32 vcc, 3, v0
	s_and_saveexec_b64 s[8:9], vcc
	s_cbranch_execz .LBB0_849
	v_subrev_u32_e32 v0, 33, v3
	v_cmp_lt_u32_e32 vcc, 2, v0
	v_mov_b32_e32 v4, 4
	s_and_saveexec_b64 s[10:11], vcc
	s_cbranch_execz .LBB0_848
	v_subrev_u32_e32 v0, 36, v3
	v_cmp_lt_u32_e32 vcc, 1, v0
	v_mov_b32_e32 v4, 5
	s_and_saveexec_b64 s[12:13], vcc
	s_cbranch_execz .LBB0_847
	v_subrev_u32_e32 v0, 38, v3
	v_cmp_lt_u32_e32 vcc, 1, v0
	v_mov_b32_e32 v4, 6
	s_and_saveexec_b64 s[24:25], vcc
	s_cbranch_execz .LBB0_846
	v_subrev_u32_e32 v0, 40, v3
	v_cmp_lt_u32_e32 vcc, 1, v0
	v_mov_b32_e32 v4, 7
	s_and_saveexec_b64 s[26:27], vcc
	s_cbranch_execz .LBB0_845
	v_subrev_u32_e32 v0, 42, v3
	v_cmp_lt_u32_e32 vcc, 7, v0
	s_and_saveexec_b64 s[28:29], vcc
	s_xor_b64 s[28:29], exec, s[28:29]
	v_subrev_u32_e32 v0, 50, v3
	s_or_saveexec_b64 s[28:29], s[28:29]
	v_mov_b32_e32 v4, 16
	s_xor_b64 exec, exec, s[28:29]
	v_subrev_u32_e32 v4, 34, v3
	v_mov_b32_e32 v0, 0
	s_or_b64 exec, exec, s[28:29]
